# priorities equalised (s_setprio 0) for the S5 sample items and the gMLP items of P2; static raise for waves 0-3 restored at P3
# baseline (speedup 1.0000x reference)
; #define GPTR(T, p) gptr_<T>(p)
; #define GIN(i) GPTR(const float, args.in[i])
; __global__ void __launch_bounds__(NWAVES * 64, 2) hymba_fwd(Args args) {
;     ...
;             for (int it = bx * NWAVES + wave; it < DECB * NG; it += G * NWAVES) { const int g = it & 31, b = it >> 5;
;                 s5_sample_wave(lane, b, g, tb, cre, cim, dsk, US, YS, GIN(I_STRE) + (size_t)L * DECB * NG * NP, GIN(I_STIM) + (size_t)L * DECB * NG * NP,
;                                GPTR(float, args.out) + O_RES + (size_t)L * DECB * NG * NP, GPTR(float, args.out) + O_IMS + (size_t)L * DECB * NG * NP); }
.LBB0_890:
	s_setprio 0
	v_readlane_b32 s61, v254, 12
	s_add_i32 s2, s56, s61
	v_readlane_b32 s64, v254, 9
	v_readlane_b32 s72, v254, 38
	v_readlane_b32 s78, v254, 17
	v_readlane_b32 s80, v254, 21
	v_readlane_b32 s88, v255, 6
	v_readlane_b32 s92, v255, 8
	s_cmpk_gt_i32 s2, 0xfff
	v_readlane_b32 s65, v254, 10
	v_readlane_b32 s73, v254, 39
	v_readlane_b32 s76, v254, 40
	v_readlane_b32 s79, v254, 18
	v_readlane_b32 s81, v254, 22
	v_readlane_b32 s82, v254, 25
	v_readlane_b32 s83, v255, 5
	v_readlane_b32 s89, v255, 7
	v_readlane_b32 s93, v255, 9
	v_readlane_b32 s77, v254, 41
	s_cbranch_scc1 .LBB0_901
	v_readlane_b32 s0, v255, 3
	v_readlane_b32 s4, v254, 5
	v_readlane_b32 s1, v255, 4
	v_readlane_b32 s5, v254, 6
	s_add_u32 s18, s4, s0
	s_addc_u32 s19, s5, s1
	v_readlane_b32 s4, v254, 3
	v_readlane_b32 s5, v254, 4
	s_add_u32 s20, s4, s0
	v_and_b32_e32 v2, 16, v192
	s_addc_u32 s21, s5, s1
	v_cmp_eq_u32_e64 s[4:5], 0, v2
	v_and_b32_e32 v2, 8, v192
	s_ashr_i32 s3, s2, 31
	v_cmp_eq_u32_e64 s[6:7], 0, v2
	v_and_b32_e32 v2, 4, v192
	s_lshl_b64 s[12:13], s[2:3], 8
	v_readlane_b32 s14, v254, 63
	v_lshrrev_b32_e32 v44, 2, v196
	v_cmp_eq_u32_e64 s[8:9], 0, v2
	v_and_b32_e32 v2, 3, v192
	v_readlane_b32 s15, v255, 0
	s_add_u32 s12, s14, s12
	v_cmp_eq_u32_e64 s[10:11], 0, v2
	v_lshlrev_b32_e32 v2, 1, v44
	s_addc_u32 s13, s15, s13
	v_lshlrev_b32_e32 v48, 2, v196
	v_mov_b32_e32 v49, v3
	v_cmp_gt_u32_e64 s[0:1], 32, v196
	v_lshl_add_u64 v[46:47], s[22:23], 0, v[2:3]
	v_lshl_add_u64 v[50:51], s[12:13], 0, v[48:49]
	s_waitcnt vmcnt(0)
	s_branch .LBB0_893

; __global__ void __launch_bounds__(NWAVES * 64, 2) hymba_fwd(Args args) {
;     ...
;         if (PHON(3) && IN(pb + 2)) {
;             PHASE_PTRS();
;             int tid = threadIdx.x; asm volatile("" : "+v"(tid)); const int lane = tid & 63, wave = __builtin_amdgcn_readfirstlane(tid >> 6);
.LBB0_990:
	v_readfirstlane_b32 s2, v0
	s_nop 3
	s_and_b32 s2, s2, 0x3ff
	s_lshr_b32 s2, s2, 6
	s_cmp_lt_u32 s2, 4
	s_cbranch_scc0 .Lprio_p3_a
	s_setprio 1
